# v58 + code placement: two 4-byte pads so that every GEMM K-loop and the attention loops sit at the baseline byte phase mod 8 (they had been shifted by 4 since the gate-table edit)
# baseline (speedup 1.0000x reference)
.LBB0_290:
	s_nop 0
	s_cmpk_gt_i32 s45, 0x5ff
	s_cbranch_scc1 .LBB0_295
	s_load_dwordx2 s[4:5], s[14:15], 0x38
	v_lshlrev_b32_e32 v0, 2, v188
	s_lshl_b32 s6, s47, 14
	v_and_b32_e32 v4, 0x7c, v0
	v_mov_b32_e32 v5, 0
	v_lshrrev_b32_e32 v7, 3, v189
	v_and_b32_e32 v2, 56, v128
	s_add_i32 s7, s6, 0
	v_lshrrev_b32_e32 v6, 5, v189
	s_waitcnt lgkmcnt(0)
	v_lshl_add_u64 v[0:1], s[4:5], 0, v[4:5]
	v_mul_u32_u24_e32 v8, 0x84, v2
	v_mov_b32_e32 v3, v5
	v_lshlrev_b32_e32 v5, 2, v7
	v_lshlrev_b32_e32 v2, 1, v2
	v_add3_u32 v8, s7, v8, v5
	v_mul_u32_u24_e32 v5, 0x84, v6
	s_add_u32 s0, s18, 0x2000
	v_lshl_add_u64 v[2:3], s[16:17], 0, v[2:3]
	s_mov_b64 s[4:5], 0x4700000
	v_or_b32_e32 v5, s6, v5
	s_addc_u32 s1, s19, 0
	v_lshl_add_u64 v[2:3], v[2:3], 0, s[4:5]
	v_or_b32_e32 v9, 8, v7
	v_or_b32_e32 v10, 16, v7
	v_or_b32_e32 v11, 24, v7
	v_add3_u32 v12, v5, v4, 0
	s_movk_i32 s8, 0x3020

.LBB0_1678:
	s_setprio 0
	s_nop 0
	s_mov_b64 s[4:5], s[74:75]
	s_getreg_b32 s8, hwreg(HW_REG_XCC_ID, 0, 4)
	s_waitcnt vmcnt(0)
	s_barrier
	s_and_saveexec_b64 s[0:1], s[78:79]
	s_cbranch_execz .LBB0_1730
	s_add_i32 s9, 0, 0x23fc0
	v_mov_b32_e32 v0, s9
	s_load_dwordx2 s[4:5], s[4:5], 0x90
	s_waitcnt vmcnt(0) expcnt(0) lgkmcnt(0)
	ds_read_b32 v2, v0
	s_add_i32 s9, 0, 0x23fc4
	v_mov_b32_e32 v0, s9
	ds_read_b32 v0, v0
	s_and_b32 s33, s8, 15
	s_waitcnt lgkmcnt(1)
	v_cmp_ne_u32_e32 vcc, 0, v2
	s_cbranch_vccnz .LBB0_1694
	s_load_dwordx2 s[12:13], s[76:77], 0x4
	s_add_u32 s8, s4, 0x5700200
	s_addc_u32 s9, s5, 0
	s_add_u32 s10, s4, 0x5700400
	s_addc_u32 s11, s5, 0
	s_waitcnt lgkmcnt(0)
	s_mul_i32 s50, s12, s90
	s_add_u32 s12, s4, 0x5700500
	s_mul_i32 s50, s50, s13
	s_addc_u32 s13, s5, 0
	s_add_u32 s14, s4, 0x5700600
	s_addc_u32 s15, s5, 0
	s_add_u32 s16, s4, 0x5700700
	s_addc_u32 s17, s5, 0
	s_add_u32 s18, s4, 0x5700800
	s_addc_u32 s19, s5, 0
	s_add_u32 s20, s4, 0x5700900
	s_addc_u32 s21, s5, 0
	s_add_u32 s22, s4, 0x5700a00
	s_addc_u32 s23, s5, 0
	s_add_u32 s24, s4, 0x5700b00
	s_addc_u32 s25, s5, 0
	s_add_u32 s26, s4, 0x5700c00
	s_addc_u32 s27, s5, 0
	s_add_u32 s28, s4, 0x5700d00
	s_addc_u32 s29, s5, 0
	s_add_u32 s30, s4, 0x5700e00
	s_addc_u32 s31, s5, 0
	s_add_u32 s34, s4, 0x5700f00
	s_addc_u32 s35, s5, 0
	s_add_u32 s36, s4, 0x5701000
	s_addc_u32 s37, s5, 0
	s_add_u32 s38, s4, 0x5701100
	s_addc_u32 s39, s5, 0
	s_add_u32 s40, s4, 0x5701200
	s_addc_u32 s41, s5, 0
	s_add_u32 s42, s4, 0x5701300
	s_addc_u32 s43, s5, 0
	s_mov_b32 s51, 1
	v_mov_b32_e32 v16, 0
	s_branch .LBB0_1682
